# stacked: rotated attention loops + S_A(0,0) DMA rebalance in in-proj/up-proj/out-proj K-loops + adaLN GEMV 16 loads in flight (all bit-identical)
# baseline (speedup 1.0000x reference)
; #define PG8_STAGE(bufoff, gbase, voff) do { _Pragma("unroll") for (int _i = 0; _i < 2; ++_i) \
;         __builtin_amdgcn_global_load_lds((const unsigned*)((const char*)(gbase) + (voff)[_i]), (LAS unsigned*)(lds + (bufoff) + ldsw + _i * 8192), 16, 0, 0); } while (0)
; #define PG8_LDA(dst, b, h) do { _Pragma("unroll") for (int m = 0; m < 4; ++m) _Pragma("unroll") for (int k = 0; k < 2; ++k) dst[m][k] = *(const LAS bf16x8*)(lds + PG8_SA(b, h) + aoff + m * 2048 + k * 1024); } while (0)
; #define PG8_LDB(dst, b, h) do { _Pragma("unroll") for (int n = 0; n < 2; ++n) _Pragma("unroll") for (int k = 0; k < 2; ++k) dst[n][k] = *(const LAS bf16x8*)(lds + PG8_SB(b, h) + boff + n * 2048 + k * 1024); } while (0)
; #define PG8_WAIT_V(n) asm volatile("s_waitcnt vmcnt(" #n ")" ::: "memory")
; #define PG8_WAIT_L(n) asm volatile("s_waitcnt lgkmcnt(" #n ")" ::: "memory")
; #define PG8_BAR __builtin_amdgcn_s_barrier()
; #define PG8_SCHED __builtin_amdgcn_sched_barrier(0)
; template <class Epi>
; __device__ __forceinline__ void gemm_phase(LAS unsigned char* lds, const Gemm g, const StaticOrder& S, const Epi& E, const int tid) {
;     ...
;         for (int t = 0; t < nt; t += 2) {
;             const bool last = (t == nt - 2);
;             const char* a1 = cA + (size_t)(t + 1) * kstep;
;             const char* a2 = last ? nA : cA + (size_t)(t + 2) * kstep; const char* b2 = last ? nB : cB + (size_t)(t + 2) * kstep;
;             const char* a3 = a2 + kstep; const char* b3 = b2 + kstep;
;             if constexpr (Epi::MID) { if (t == 16 || t == 32) { int fr_ = fr, fq_ = fq, wr_ = wr, wc_ = wc;
;                 asm volatile("" : "+v"(fr_), "+v"(fq_)); asm volatile("" : "+s"(wr_), "+s"(wc_));
;                 E.mid(acc, cur, t >> 4, wr_, wc_, fr_, fq_); PG8_WAIT_V(0); PG8_SCHED; } }
;             PG8_LDB(B0, 0, 0); PG8_LDB(B1, 0, 1); PG8_SCHED; PG8_LDA(At, 0, 0); PG8_STAGE(PG8_SA(1, 1), a1 + hstep, voffA);
;             PG8_WAIT_V(8); PG8_WAIT_L(0); PG8_BAR; PG8_MMA(0, 0, At, B0); PG8_MMA(0, 1, At, B1); PG8_BAR; PG8_SCHED;
;             PG8_LDA(At, 0, 1); PG8_STAGE(PG8_SB(0, 0), b2, voffB); PG8_STAGE(PG8_SB(0, 1), b2 + hstep, voffB); PG8_STAGE(PG8_SA(0, 0), a2, voffA);
;             PG8_WAIT_V(8); PG8_WAIT_L(0); PG8_BAR; PG8_MMA(1, 0, At, B0); PG8_MMA(1, 1, At, B1); PG8_BAR; PG8_SCHED;
.LBB0_29:
	s_add_u32 s60, s58, 0xfffe0080
	s_addc_u32 s61, s59, -1
	s_add_i32 s71, 0, 0x10000
	s_cmp_eq_u32 s47, 4
	s_cselect_b32 s63, s3, s61
	s_cselect_b32 s62, s4, s60
	s_cselect_b32 s61, s5, s45
	s_cselect_b32 s60, s35, s37
	s_add_i32 s75, 0, 0x14000
	v_add_u32_e32 v140, s71, v187
	v_add_u32_e32 v166, s75, v187
	s_waitcnt lgkmcnt(0)
	ds_read_b128 v[128:131], v140
	ds_read_b128 v[132:135], v140 offset:1024
	ds_read_b128 v[136:139], v140 offset:2048
	ds_read_b128 v[140:143], v140 offset:3072
	ds_read_b128 v[154:157], v166
	ds_read_b128 v[158:161], v166 offset:1024
	ds_read_b128 v[162:165], v166 offset:2048
	ds_read_b128 v[166:169], v166 offset:3072
	v_lshl_add_u64 v[174:175], s[58:59], 0, v[150:151]
	s_add_i32 m0, s64, 0xc000
	ds_read_b128 v[170:173], v191
	ds_read_b128 v[192:195], v191 offset:1024
	ds_read_b128 v[196:199], v191 offset:2048
	ds_read_b128 v[200:203], v191 offset:3072
	ds_read_b128 v[204:207], v191 offset:4096
	ds_read_b128 v[208:211], v191 offset:5120
	ds_read_b128 v[212:215], v191 offset:6144
	ds_read_b128 v[216:219], v191 offset:7168
	global_load_lds_dwordx4 v[174:175], off
	v_lshl_add_u64 v[174:175], s[58:59], 0, v[152:153]
	s_add_i32 m0, s64, 0xe000
	s_nop 0
	global_load_lds_dwordx4 v[174:175], off
	s_waitcnt vmcnt(8)
	s_waitcnt lgkmcnt(0)
	s_barrier
	s_setprio 1
	s_waitcnt lgkmcnt(0)
	v_mfma_f32_16x16x32_bf16 v[124:127], v[128:131], v[170:173], v[124:127]
	v_mfma_f32_16x16x32_bf16 v[108:111], v[136:139], v[170:173], v[108:111]
	v_mfma_f32_16x16x32_bf16 v[116:119], v[128:131], v[196:199], v[116:119]
	v_mfma_f32_16x16x32_bf16 v[104:107], v[136:139], v[196:199], v[104:107]
	v_mfma_f32_16x16x32_bf16 v[92:95], v[128:131], v[204:207], v[92:95]
	v_mfma_f32_16x16x32_bf16 v[80:83], v[136:139], v[204:207], v[80:83]
	v_mfma_f32_16x16x32_bf16 v[88:91], v[128:131], v[212:215], v[88:91]
	v_mfma_f32_16x16x32_bf16 v[72:75], v[136:139], v[212:215], v[72:75]
	v_mfma_f32_16x16x32_bf16 v[124:127], v[132:135], v[192:195], v[124:127]
	v_mfma_f32_16x16x32_bf16 v[108:111], v[140:143], v[192:195], v[108:111]
	v_mfma_f32_16x16x32_bf16 v[116:119], v[132:135], v[200:203], v[116:119]
	v_mfma_f32_16x16x32_bf16 v[104:107], v[140:143], v[200:203], v[104:107]
	v_mfma_f32_16x16x32_bf16 v[92:95], v[132:135], v[208:211], v[92:95]
	v_mfma_f32_16x16x32_bf16 v[80:83], v[140:143], v[208:211], v[80:83]
	v_mfma_f32_16x16x32_bf16 v[88:91], v[132:135], v[216:219], v[88:91]
	v_mfma_f32_16x16x32_bf16 v[72:75], v[140:143], v[216:219], v[72:75]
	s_setprio 0
	s_setprio 1
	v_mfma_f32_16x16x32_bf16 v[120:123], v[154:157], v[170:173], v[120:123]
	v_mfma_f32_16x16x32_bf16 v[100:103], v[162:165], v[170:173], v[100:103]
	v_mfma_f32_16x16x32_bf16 v[112:115], v[154:157], v[196:199], v[112:115]
	v_mfma_f32_16x16x32_bf16 v[96:99], v[162:165], v[196:199], v[96:99]
	v_mfma_f32_16x16x32_bf16 v[84:87], v[154:157], v[204:207], v[84:87]
	v_mfma_f32_16x16x32_bf16 v[68:71], v[162:165], v[204:207], v[68:71]
	v_mfma_f32_16x16x32_bf16 v[76:79], v[154:157], v[212:215], v[76:79]
	v_mfma_f32_16x16x32_bf16 v[64:67], v[162:165], v[212:215], v[64:67]
	v_mfma_f32_16x16x32_bf16 v[120:123], v[158:161], v[192:195], v[120:123]
	v_mfma_f32_16x16x32_bf16 v[100:103], v[166:169], v[192:195], v[100:103]
	v_mfma_f32_16x16x32_bf16 v[112:115], v[158:161], v[200:203], v[112:115]
	v_mfma_f32_16x16x32_bf16 v[96:99], v[166:169], v[200:203], v[96:99]
	v_mfma_f32_16x16x32_bf16 v[84:87], v[158:161], v[208:211], v[84:87]
	v_mfma_f32_16x16x32_bf16 v[68:71], v[166:169], v[208:211], v[68:71]
	v_mfma_f32_16x16x32_bf16 v[76:79], v[158:161], v[216:219], v[76:79]
	v_mfma_f32_16x16x32_bf16 v[64:67], v[166:169], v[216:219], v[64:67]
	s_setprio 0
	s_barrier
	s_add_i32 s71, s71, s42
	v_lshl_add_u64 v[174:175], s[60:61], 0, v[176:177]
	s_mov_b32 m0, s71
	ds_read_b128 v[170:173], v191 offset:16384
	ds_read_b128 v[192:195], v191 offset:17408
	ds_read_b128 v[196:199], v191 offset:18432
	ds_read_b128 v[200:203], v191 offset:19456
	ds_read_b128 v[204:207], v191 offset:20480
	ds_read_b128 v[208:211], v191 offset:21504
	ds_read_b128 v[212:215], v191 offset:22528
	ds_read_b128 v[216:219], v191 offset:23552
	global_load_lds_dwordx4 v[174:175], off
	s_add_i32 m0, s71, 0x2000
	s_add_u32 s72, s60, 0x20000
	v_lshl_add_u64 v[184:185], s[60:61], 0, v[144:145]
	s_addc_u32 s73, s61, 0
	s_add_i32 s71, s75, s42
	global_load_lds_dwordx4 v[184:185], off
	v_lshl_add_u64 v[220:221], s[72:73], 0, v[176:177]
	s_mov_b32 m0, s71
	v_lshl_add_u64 v[222:223], s[62:63], 0, v[146:147]
	global_load_lds_dwordx4 v[220:221], off
	v_lshl_add_u64 v[220:221], s[72:73], 0, v[144:145]
	s_add_i32 m0, s71, 0x2000
	s_nop 0
	global_load_lds_dwordx4 v[220:221], off
	v_lshl_add_u64 v[220:221], s[62:63], 0, v[148:149]
	s_waitcnt vmcnt(6)
	s_waitcnt lgkmcnt(0)
	s_barrier
; #define PG8_STAGE(bufoff, gbase, voff) do { _Pragma("unroll") for (int _i = 0; _i < 2; ++_i) \
;         __builtin_amdgcn_global_load_lds((const unsigned*)((const char*)(gbase) + (voff)[_i]), (LAS unsigned*)(lds + (bufoff) + ldsw + _i * 8192), 16, 0, 0); } while (0)
; #define PG8_LDA(dst, b, h) do { _Pragma("unroll") for (int m = 0; m < 4; ++m) _Pragma("unroll") for (int k = 0; k < 2; ++k) dst[m][k] = *(const LAS bf16x8*)(lds + PG8_SA(b, h) + aoff + m * 2048 + k * 1024); } while (0)
; #define PG8_LDB(dst, b, h) do { _Pragma("unroll") for (int n = 0; n < 2; ++n) _Pragma("unroll") for (int k = 0; k < 2; ++k) dst[n][k] = *(const LAS bf16x8*)(lds + PG8_SB(b, h) + boff + n * 2048 + k * 1024); } while (0)
; #define PG8_MMA(ai, bj, At, Bt) do { __builtin_amdgcn_s_setprio(1); _Pragma("unroll") for (int m = 0; m < 4; ++m) _Pragma("unroll") for (int n = 0; n < 2; ++n) _Pragma("unroll") for (int k = 0; k < 2; ++k) \
;         acc[ai][bj][m][n] = __builtin_amdgcn_mfma_f32_16x16x32_bf16(Bt[n][k], At[m][k], acc[ai][bj][m][n], 0, 0, 0); __builtin_amdgcn_s_setprio(0); } while (0)
; #define PG8_WAIT_V(n) asm volatile("s_waitcnt vmcnt(" #n ")" ::: "memory")
; #define PG8_WAIT_L(n) asm volatile("s_waitcnt lgkmcnt(" #n ")" ::: "memory")
; #define PG8_BAR __builtin_amdgcn_s_barrier()
; #define PG8_SCHED __builtin_amdgcn_sched_barrier(0)
; template <class Epi>
; __device__ __forceinline__ void gemm_phase(LAS unsigned char* lds, const Gemm g, const StaticOrder& S, const Epi& E, const int tid) {
;     ...
;             PG8_WAIT_V(8); PG8_WAIT_L(0); PG8_BAR; PG8_MMA(1, 0, At, B0); PG8_MMA(1, 1, At, B1); PG8_BAR; PG8_SCHED;
;             PG8_LDB(B0, 1, 0); PG8_LDB(B1, 1, 1); PG8_SCHED; PG8_LDA(At, 1, 0); PG8_STAGE(PG8_SA(0, 1), a2 + hstep, voffA);
;             PG8_WAIT_V(8); PG8_WAIT_L(0); PG8_BAR; PG8_MMA(0, 0, At, B0); PG8_MMA(0, 1, At, B1); PG8_BAR; PG8_SCHED;
	s_setprio 1
	s_waitcnt lgkmcnt(0)
	v_mfma_f32_16x16x32_bf16 v[60:63], v[128:131], v[170:173], v[60:63]
	v_mfma_f32_16x16x32_bf16 v[48:51], v[136:139], v[170:173], v[48:51]
	v_mfma_f32_16x16x32_bf16 v[56:59], v[128:131], v[196:199], v[56:59]
	v_mfma_f32_16x16x32_bf16 v[40:43], v[136:139], v[196:199], v[40:43]
	v_mfma_f32_16x16x32_bf16 v[28:31], v[128:131], v[204:207], v[28:31]
	v_mfma_f32_16x16x32_bf16 v[16:19], v[136:139], v[204:207], v[16:19]
	v_mfma_f32_16x16x32_bf16 v[24:27], v[128:131], v[212:215], v[24:27]
	v_mfma_f32_16x16x32_bf16 v[8:11], v[136:139], v[212:215], v[8:11]
	v_mfma_f32_16x16x32_bf16 v[60:63], v[132:135], v[192:195], v[60:63]
	v_mfma_f32_16x16x32_bf16 v[48:51], v[140:143], v[192:195], v[48:51]
	v_mfma_f32_16x16x32_bf16 v[56:59], v[132:135], v[200:203], v[56:59]
	v_mfma_f32_16x16x32_bf16 v[40:43], v[140:143], v[200:203], v[40:43]
	v_mfma_f32_16x16x32_bf16 v[28:31], v[132:135], v[208:211], v[28:31]
	v_mfma_f32_16x16x32_bf16 v[16:19], v[140:143], v[208:211], v[16:19]
	v_mfma_f32_16x16x32_bf16 v[24:27], v[132:135], v[216:219], v[24:27]
	v_mfma_f32_16x16x32_bf16 v[8:11], v[140:143], v[216:219], v[8:11]
	s_setprio 0
	s_setprio 1
	v_mfma_f32_16x16x32_bf16 v[52:55], v[154:157], v[170:173], v[52:55]
	v_mfma_f32_16x16x32_bf16 v[36:39], v[162:165], v[170:173], v[36:39]
	v_mfma_f32_16x16x32_bf16 v[44:47], v[154:157], v[196:199], v[44:47]
	v_mfma_f32_16x16x32_bf16 v[32:35], v[162:165], v[196:199], v[32:35]
	v_mfma_f32_16x16x32_bf16 v[20:23], v[154:157], v[204:207], v[20:23]
	v_mfma_f32_16x16x32_bf16 v[4:7], v[162:165], v[204:207], v[4:7]
	v_mfma_f32_16x16x32_bf16 v[12:15], v[154:157], v[212:215], v[12:15]
	v_mfma_f32_16x16x32_bf16 v[0:3], v[162:165], v[212:215], v[0:3]
	v_mfma_f32_16x16x32_bf16 v[52:55], v[158:161], v[192:195], v[52:55]
	v_mfma_f32_16x16x32_bf16 v[36:39], v[166:169], v[192:195], v[36:39]
	v_mfma_f32_16x16x32_bf16 v[44:47], v[158:161], v[200:203], v[44:47]
	v_mfma_f32_16x16x32_bf16 v[32:35], v[166:169], v[200:203], v[32:35]
	v_mfma_f32_16x16x32_bf16 v[20:23], v[158:161], v[208:211], v[20:23]
	v_mfma_f32_16x16x32_bf16 v[4:7], v[166:169], v[208:211], v[4:7]
	v_mfma_f32_16x16x32_bf16 v[12:15], v[158:161], v[216:219], v[12:15]
	v_mfma_f32_16x16x32_bf16 v[0:3], v[166:169], v[216:219], v[0:3]
	s_setprio 0
	s_barrier
	s_add_i32 s71, 0, 0x18000
	s_add_i32 s72, 0, 0x1c000
	v_add_u32_e32 v140, s71, v187
	v_add_u32_e32 v166, s72, v187
	ds_read_b128 v[128:131], v140
	ds_read_b128 v[132:135], v140 offset:1024
	ds_read_b128 v[136:139], v140 offset:2048
	ds_read_b128 v[140:143], v140 offset:3072
	ds_read_b128 v[154:157], v166
	ds_read_b128 v[158:161], v166 offset:1024
	ds_read_b128 v[162:165], v166 offset:2048
	ds_read_b128 v[166:169], v166 offset:3072
	s_add_u32 s62, s62, 0x20000
	s_addc_u32 s63, s63, 0
	s_mov_b32 m0, s64
	s_nop 0
	global_load_lds_dwordx4 v[220:221], off
	s_mov_b32 m0, s65
	s_nop 0
	global_load_lds_dwordx4 v[222:223], off
	s_mov_b32 m0, s66
	v_lshl_add_u64 v[224:225], s[62:63], 0, v[148:149]
	ds_read_b128 v[170:173], v191 offset:32768
	ds_read_b128 v[192:195], v191 offset:33792
	ds_read_b128 v[196:199], v191 offset:34816
	ds_read_b128 v[200:203], v191 offset:35840
	ds_read_b128 v[204:207], v191 offset:36864
	ds_read_b128 v[208:211], v191 offset:37888
	ds_read_b128 v[212:215], v191 offset:38912
	ds_read_b128 v[216:219], v191 offset:39936
	global_load_lds_dwordx4 v[224:225], off
	v_lshl_add_u64 v[224:225], s[62:63], 0, v[146:147]
	s_mov_b32 m0, s67
	s_nop 0
	global_load_lds_dwordx4 v[224:225], off
	s_waitcnt vmcnt(8)
	s_waitcnt lgkmcnt(0)
	s_barrier
	s_setprio 1
	s_waitcnt lgkmcnt(0)
	v_mfma_f32_16x16x32_bf16 v[124:127], v[128:131], v[170:173], v[124:127]
	v_mfma_f32_16x16x32_bf16 v[108:111], v[136:139], v[170:173], v[108:111]
	v_mfma_f32_16x16x32_bf16 v[116:119], v[128:131], v[196:199], v[116:119]
	v_mfma_f32_16x16x32_bf16 v[104:107], v[136:139], v[196:199], v[104:107]
	v_mfma_f32_16x16x32_bf16 v[92:95], v[128:131], v[204:207], v[92:95]
	v_mfma_f32_16x16x32_bf16 v[80:83], v[136:139], v[204:207], v[80:83]
	v_mfma_f32_16x16x32_bf16 v[88:91], v[128:131], v[212:215], v[88:91]
	v_mfma_f32_16x16x32_bf16 v[72:75], v[136:139], v[212:215], v[72:75]
	v_mfma_f32_16x16x32_bf16 v[124:127], v[132:135], v[192:195], v[124:127]
	v_mfma_f32_16x16x32_bf16 v[108:111], v[140:143], v[192:195], v[108:111]
	v_mfma_f32_16x16x32_bf16 v[116:119], v[132:135], v[200:203], v[116:119]
	v_mfma_f32_16x16x32_bf16 v[104:107], v[140:143], v[200:203], v[104:107]
	v_mfma_f32_16x16x32_bf16 v[92:95], v[132:135], v[208:211], v[92:95]
	v_mfma_f32_16x16x32_bf16 v[80:83], v[140:143], v[208:211], v[80:83]
	v_mfma_f32_16x16x32_bf16 v[88:91], v[132:135], v[216:219], v[88:91]
	v_mfma_f32_16x16x32_bf16 v[72:75], v[140:143], v[216:219], v[72:75]
	s_setprio 0
	s_setprio 1
	v_mfma_f32_16x16x32_bf16 v[120:123], v[154:157], v[170:173], v[120:123]
	v_mfma_f32_16x16x32_bf16 v[100:103], v[162:165], v[170:173], v[100:103]
	v_mfma_f32_16x16x32_bf16 v[112:115], v[154:157], v[196:199], v[112:115]
	v_mfma_f32_16x16x32_bf16 v[96:99], v[162:165], v[196:199], v[96:99]
	v_mfma_f32_16x16x32_bf16 v[84:87], v[154:157], v[204:207], v[84:87]
	v_mfma_f32_16x16x32_bf16 v[68:71], v[162:165], v[204:207], v[68:71]
	v_mfma_f32_16x16x32_bf16 v[76:79], v[154:157], v[212:215], v[76:79]
	v_mfma_f32_16x16x32_bf16 v[64:67], v[162:165], v[212:215], v[64:67]
	v_mfma_f32_16x16x32_bf16 v[120:123], v[158:161], v[192:195], v[120:123]
	v_mfma_f32_16x16x32_bf16 v[100:103], v[166:169], v[192:195], v[100:103]
	v_mfma_f32_16x16x32_bf16 v[112:115], v[158:161], v[200:203], v[112:115]
	v_mfma_f32_16x16x32_bf16 v[96:99], v[166:169], v[200:203], v[96:99]
	v_mfma_f32_16x16x32_bf16 v[84:87], v[158:161], v[208:211], v[84:87]
	v_mfma_f32_16x16x32_bf16 v[68:71], v[166:169], v[208:211], v[68:71]
	v_mfma_f32_16x16x32_bf16 v[76:79], v[158:161], v[216:219], v[76:79]
	v_mfma_f32_16x16x32_bf16 v[64:67], v[166:169], v[216:219], v[64:67]
	s_setprio 0
	s_barrier
; #define PG8_STAGE(bufoff, gbase, voff) do { _Pragma("unroll") for (int _i = 0; _i < 2; ++_i) \
;         __builtin_amdgcn_global_load_lds((const unsigned*)((const char*)(gbase) + (voff)[_i]), (LAS unsigned*)(lds + (bufoff) + ldsw + _i * 8192), 16, 0, 0); } while (0)
; #define PG8_LDA(dst, b, h) do { _Pragma("unroll") for (int m = 0; m < 4; ++m) _Pragma("unroll") for (int k = 0; k < 2; ++k) dst[m][k] = *(const LAS bf16x8*)(lds + PG8_SA(b, h) + aoff + m * 2048 + k * 1024); } while (0)
; #define PG8_MMA(ai, bj, At, Bt) do { __builtin_amdgcn_s_setprio(1); _Pragma("unroll") for (int m = 0; m < 4; ++m) _Pragma("unroll") for (int n = 0; n < 2; ++n) _Pragma("unroll") for (int k = 0; k < 2; ++k) \
;         acc[ai][bj][m][n] = __builtin_amdgcn_mfma_f32_16x16x32_bf16(Bt[n][k], At[m][k], acc[ai][bj][m][n], 0, 0, 0); __builtin_amdgcn_s_setprio(0); } while (0)
; #define PG8_WAIT_V(n) asm volatile("s_waitcnt vmcnt(" #n ")" ::: "memory")
; #define PG8_WAIT_L(n) asm volatile("s_waitcnt lgkmcnt(" #n ")" ::: "memory")
; #define PG8_BAR __builtin_amdgcn_s_barrier()
; #define PG8_SCHED __builtin_amdgcn_sched_barrier(0)
; template <class Epi>
; __device__ __forceinline__ void gemm_phase(LAS unsigned char* lds, const Gemm g, const StaticOrder& S, const Epi& E, const int tid) {
;     ...
;             PG8_LDA(At, 1, 1); PG8_STAGE(PG8_SB(1, 0), b3, voffB); PG8_STAGE(PG8_SB(1, 1), b3 + hstep, voffB); PG8_STAGE(PG8_SA(1, 0), a3, voffA);
;             PG8_WAIT_V(8); PG8_WAIT_L(0); PG8_BAR; PG8_MMA(1, 0, At, B0); PG8_MMA(1, 1, At, B1); PG8_BAR; PG8_SCHED;
;         }
;         if (wr == 0) PG8_BAR;
	s_add_i32 s62, s71, s42
	v_lshl_add_u64 v[174:175], v[174:175], 0, s[0:1]
	s_mov_b32 m0, s62
	ds_read_b128 v[170:173], v191 offset:49152
	ds_read_b128 v[192:195], v191 offset:50176
	ds_read_b128 v[196:199], v191 offset:51200
	ds_read_b128 v[200:203], v191 offset:52224
	ds_read_b128 v[204:207], v191 offset:53248
	ds_read_b128 v[208:211], v191 offset:54272
	ds_read_b128 v[212:215], v191 offset:55296
	ds_read_b128 v[216:219], v191 offset:56320
	global_load_lds_dwordx4 v[174:175], off
	s_add_i32 m0, s62, 0x2000
	s_add_u32 s60, s60, 0x20080
	v_lshl_add_u64 v[174:175], v[184:185], 0, s[0:1]
	s_addc_u32 s61, s61, 0
	s_add_i32 s62, s72, s42
	global_load_lds_dwordx4 v[174:175], off
	v_lshl_add_u64 v[174:175], s[60:61], 0, v[176:177]
	s_mov_b32 m0, s62
	s_nop 0
	global_load_lds_dwordx4 v[174:175], off
	v_lshl_add_u64 v[174:175], s[60:61], 0, v[144:145]
	s_add_i32 m0, s62, 0x2000
	s_nop 0
	global_load_lds_dwordx4 v[174:175], off
	v_lshl_add_u64 v[174:175], v[220:221], 0, s[0:1]
	s_mov_b32 m0, s68
	s_nop 0
	global_load_lds_dwordx4 v[174:175], off
	v_lshl_add_u64 v[174:175], v[222:223], 0, s[0:1]
	s_mov_b32 m0, s69
	s_nop 0
	global_load_lds_dwordx4 v[174:175], off
	s_waitcnt vmcnt(8)
	s_waitcnt lgkmcnt(0)
	s_barrier
	s_setprio 1
	s_waitcnt lgkmcnt(0)
	v_mfma_f32_16x16x32_bf16 v[60:63], v[128:131], v[170:173], v[60:63]
	v_mfma_f32_16x16x32_bf16 v[48:51], v[136:139], v[170:173], v[48:51]
	v_mfma_f32_16x16x32_bf16 v[56:59], v[128:131], v[196:199], v[56:59]
	v_mfma_f32_16x16x32_bf16 v[40:43], v[136:139], v[196:199], v[40:43]
	v_mfma_f32_16x16x32_bf16 v[28:31], v[128:131], v[204:207], v[28:31]
	v_mfma_f32_16x16x32_bf16 v[16:19], v[136:139], v[204:207], v[16:19]
	v_mfma_f32_16x16x32_bf16 v[24:27], v[128:131], v[212:215], v[24:27]
	v_mfma_f32_16x16x32_bf16 v[8:11], v[136:139], v[212:215], v[8:11]
	v_mfma_f32_16x16x32_bf16 v[60:63], v[132:135], v[192:195], v[60:63]
	v_mfma_f32_16x16x32_bf16 v[48:51], v[140:143], v[192:195], v[48:51]
	v_mfma_f32_16x16x32_bf16 v[56:59], v[132:135], v[200:203], v[56:59]
	v_mfma_f32_16x16x32_bf16 v[40:43], v[140:143], v[200:203], v[40:43]
	v_mfma_f32_16x16x32_bf16 v[28:31], v[132:135], v[208:211], v[28:31]
	v_mfma_f32_16x16x32_bf16 v[16:19], v[140:143], v[208:211], v[16:19]
	v_mfma_f32_16x16x32_bf16 v[24:27], v[132:135], v[216:219], v[24:27]
	v_mfma_f32_16x16x32_bf16 v[8:11], v[140:143], v[216:219], v[8:11]
	s_setprio 0
	s_setprio 1
	v_mfma_f32_16x16x32_bf16 v[52:55], v[154:157], v[170:173], v[52:55]
	v_mfma_f32_16x16x32_bf16 v[36:39], v[162:165], v[170:173], v[36:39]
	v_mfma_f32_16x16x32_bf16 v[44:47], v[154:157], v[196:199], v[44:47]
	v_mfma_f32_16x16x32_bf16 v[32:35], v[162:165], v[196:199], v[32:35]
	v_mfma_f32_16x16x32_bf16 v[20:23], v[154:157], v[204:207], v[20:23]
	v_mfma_f32_16x16x32_bf16 v[4:7], v[162:165], v[204:207], v[4:7]
	v_mfma_f32_16x16x32_bf16 v[12:15], v[154:157], v[212:215], v[12:15]
	v_mfma_f32_16x16x32_bf16 v[0:3], v[162:165], v[212:215], v[0:3]
	v_mfma_f32_16x16x32_bf16 v[52:55], v[158:161], v[192:195], v[52:55]
	v_mfma_f32_16x16x32_bf16 v[36:39], v[166:169], v[192:195], v[36:39]
	v_mfma_f32_16x16x32_bf16 v[44:47], v[158:161], v[200:203], v[44:47]
	v_mfma_f32_16x16x32_bf16 v[32:35], v[166:169], v[200:203], v[32:35]
	v_mfma_f32_16x16x32_bf16 v[20:23], v[158:161], v[208:211], v[20:23]
	v_mfma_f32_16x16x32_bf16 v[4:7], v[166:169], v[208:211], v[4:7]
	v_mfma_f32_16x16x32_bf16 v[12:15], v[158:161], v[216:219], v[12:15]
	v_mfma_f32_16x16x32_bf16 v[0:3], v[166:169], v[216:219], v[0:3]
	s_setprio 0
	s_barrier
	s_add_i32 s47, s47, 2
	s_add_u32 s58, s58, 0x100
	s_addc_u32 s59, s59, 0
	s_add_u32 s37, s37, 0x100
	s_addc_u32 s45, s45, 0
	s_cmp_gt_u32 s47, 5
	s_cbranch_scc0 .LBB0_29
	s_and_b64 vcc, exec, s[30:31]
	s_cbranch_vccz .LBB0_32
	s_barrier

; #define PG8_STAGE(bufoff, gbase, voff) do { _Pragma("unroll") for (int _i = 0; _i < 2; ++_i) \
;         __builtin_amdgcn_global_load_lds((const unsigned*)((const char*)(gbase) + (voff)[_i]), (LAS unsigned*)(lds + (bufoff) + ldsw + _i * 8192), 16, 0, 0); } while (0)
; #define PG8_LDA(dst, b, h) do { _Pragma("unroll") for (int m = 0; m < 4; ++m) _Pragma("unroll") for (int k = 0; k < 2; ++k) dst[m][k] = *(const LAS bf16x8*)(lds + PG8_SA(b, h) + aoff + m * 2048 + k * 1024); } while (0)
; #define PG8_LDB(dst, b, h) do { _Pragma("unroll") for (int n = 0; n < 2; ++n) _Pragma("unroll") for (int k = 0; k < 2; ++k) dst[n][k] = *(const LAS bf16x8*)(lds + PG8_SB(b, h) + boff + n * 2048 + k * 1024); } while (0)
; #define PG8_WAIT_V(n) asm volatile("s_waitcnt vmcnt(" #n ")" ::: "memory")
; #define PG8_WAIT_L(n) asm volatile("s_waitcnt lgkmcnt(" #n ")" ::: "memory")
; #define PG8_BAR __builtin_amdgcn_s_barrier()
; #define PG8_SCHED __builtin_amdgcn_sched_barrier(0)
; template <class Epi>
; __device__ __forceinline__ void gemm_phase(LAS unsigned char* lds, const Gemm g, const StaticOrder& S, const Epi& E, const int tid) {
;     ...
;         for (int t = 0; t < nt; t += 2) {
;             const bool last = (t == nt - 2);
;             const char* a1 = cA + (size_t)(t + 1) * kstep;
;             const char* a2 = last ? nA : cA + (size_t)(t + 2) * kstep; const char* b2 = last ? nB : cB + (size_t)(t + 2) * kstep;
;             const char* a3 = a2 + kstep; const char* b3 = b2 + kstep;
;             if constexpr (Epi::MID) { if (t == 16 || t == 32) { int fr_ = fr, fq_ = fq, wr_ = wr, wc_ = wc;
;                 asm volatile("" : "+v"(fr_), "+v"(fq_)); asm volatile("" : "+s"(wr_), "+s"(wc_));
;                 E.mid(acc, cur, t >> 4, wr_, wc_, fr_, fq_); PG8_WAIT_V(0); PG8_SCHED; } }
;             PG8_LDB(B0, 0, 0); PG8_LDB(B1, 0, 1); PG8_SCHED; PG8_LDA(At, 0, 0); PG8_STAGE(PG8_SA(1, 1), a1 + hstep, voffA);
;             PG8_WAIT_V(8); PG8_WAIT_L(0); PG8_BAR; PG8_MMA(0, 0, At, B0); PG8_MMA(0, 1, At, B1); PG8_BAR; PG8_SCHED;
;             PG8_LDA(At, 0, 1); PG8_STAGE(PG8_SB(0, 0), b2, voffB); PG8_STAGE(PG8_SB(0, 1), b2 + hstep, voffB); PG8_STAGE(PG8_SA(0, 0), a2, voffA);
;             PG8_WAIT_V(8); PG8_WAIT_L(0); PG8_BAR; PG8_MMA(1, 0, At, B0); PG8_MMA(1, 1, At, B1); PG8_BAR; PG8_SCHED;
.LBB0_584:
	s_add_u32 s28, s68, 0xfff80080
	s_addc_u32 s29, s69, -1
	s_add_i32 s20, 0, 0x10000
	s_cmp_eq_u32 vcc_hi, 28
	s_cselect_b32 s73, s15, s29
	s_cselect_b32 s72, s59, s28
	s_cselect_b32 s71, s61, vcc_lo
	s_cselect_b32 s70, s63, s95
	s_add_i32 s5, 0, 0x14000
	v_add_u32_e32 v156, s20, v154
	v_add_u32_e32 v172, s5, v154
	s_waitcnt lgkmcnt(0)
	ds_read_b128 v[128:131], v156
	ds_read_b128 v[132:135], v156 offset:1024
	ds_read_b128 v[146:149], v156 offset:2048
	ds_read_b128 v[156:159], v156 offset:3072
	ds_read_b128 v[160:163], v172
	ds_read_b128 v[164:167], v172 offset:1024
	ds_read_b128 v[168:171], v172 offset:2048
	ds_read_b128 v[172:175], v172 offset:3072
	v_lshl_add_u64 v[184:185], s[68:69], 0, v[142:143]
	s_add_i32 m0, s77, 0xc000
	ds_read_b128 v[192:195], v155
	ds_read_b128 v[196:199], v155 offset:1024
	ds_read_b128 v[200:203], v155 offset:2048
	ds_read_b128 v[204:207], v155 offset:3072
	ds_read_b128 v[208:211], v155 offset:4096
	ds_read_b128 v[212:215], v155 offset:5120
	ds_read_b128 v[216:219], v155 offset:6144
	ds_read_b128 v[220:223], v155 offset:7168
	global_load_lds_dwordx4 v[184:185], off
	v_lshl_add_u64 v[184:185], s[68:69], 0, v[144:145]
	s_add_i32 m0, s77, 0xe000
	s_nop 0
	global_load_lds_dwordx4 v[184:185], off
	s_waitcnt vmcnt(8)
	s_waitcnt lgkmcnt(0)
	s_barrier
	s_setprio 1
	s_waitcnt lgkmcnt(0)
	v_mfma_f32_16x16x32_bf16 v[124:127], v[128:131], v[192:195], v[124:127]
	v_mfma_f32_16x16x32_bf16 v[120:123], v[146:149], v[192:195], v[120:123]
	v_mfma_f32_16x16x32_bf16 v[116:119], v[128:131], v[200:203], v[116:119]
	v_mfma_f32_16x16x32_bf16 v[112:115], v[146:149], v[200:203], v[112:115]
	v_mfma_f32_16x16x32_bf16 v[108:111], v[128:131], v[208:211], v[108:111]
	v_mfma_f32_16x16x32_bf16 v[104:107], v[146:149], v[208:211], v[104:107]
	v_mfma_f32_16x16x32_bf16 v[100:103], v[128:131], v[216:219], v[100:103]
	v_mfma_f32_16x16x32_bf16 v[96:99], v[146:149], v[216:219], v[96:99]
	v_mfma_f32_16x16x32_bf16 v[124:127], v[132:135], v[196:199], v[124:127]
	v_mfma_f32_16x16x32_bf16 v[120:123], v[156:159], v[196:199], v[120:123]
	v_mfma_f32_16x16x32_bf16 v[116:119], v[132:135], v[204:207], v[116:119]
	v_mfma_f32_16x16x32_bf16 v[112:115], v[156:159], v[204:207], v[112:115]
	v_mfma_f32_16x16x32_bf16 v[108:111], v[132:135], v[212:215], v[108:111]
	v_mfma_f32_16x16x32_bf16 v[104:107], v[156:159], v[212:215], v[104:107]
	v_mfma_f32_16x16x32_bf16 v[100:103], v[132:135], v[220:223], v[100:103]
	v_mfma_f32_16x16x32_bf16 v[96:99], v[156:159], v[220:223], v[96:99]
	s_setprio 0
	s_setprio 1
	v_mfma_f32_16x16x32_bf16 v[60:63], v[160:163], v[192:195], v[60:63]
	v_mfma_f32_16x16x32_bf16 v[56:59], v[168:171], v[192:195], v[56:59]
	v_mfma_f32_16x16x32_bf16 v[52:55], v[160:163], v[200:203], v[52:55]
	v_mfma_f32_16x16x32_bf16 v[48:51], v[168:171], v[200:203], v[48:51]
	v_mfma_f32_16x16x32_bf16 v[44:47], v[160:163], v[208:211], v[44:47]
	v_mfma_f32_16x16x32_bf16 v[40:43], v[168:171], v[208:211], v[40:43]
	v_mfma_f32_16x16x32_bf16 v[36:39], v[160:163], v[216:219], v[36:39]
	v_mfma_f32_16x16x32_bf16 v[32:35], v[168:171], v[216:219], v[32:35]
	v_mfma_f32_16x16x32_bf16 v[60:63], v[164:167], v[196:199], v[60:63]
	v_mfma_f32_16x16x32_bf16 v[56:59], v[172:175], v[196:199], v[56:59]
	v_mfma_f32_16x16x32_bf16 v[52:55], v[164:167], v[204:207], v[52:55]
	v_mfma_f32_16x16x32_bf16 v[48:51], v[172:175], v[204:207], v[48:51]
	v_mfma_f32_16x16x32_bf16 v[44:47], v[164:167], v[212:215], v[44:47]
	v_mfma_f32_16x16x32_bf16 v[40:43], v[172:175], v[212:215], v[40:43]
	v_mfma_f32_16x16x32_bf16 v[36:39], v[164:167], v[220:223], v[36:39]
	v_mfma_f32_16x16x32_bf16 v[32:35], v[172:175], v[220:223], v[32:35]
	s_setprio 0
	s_barrier
	s_add_i32 s20, s20, s76
	v_lshl_add_u64 v[184:185], s[70:71], 0, v[176:177]
	s_mov_b32 m0, s20
	ds_read_b128 v[192:195], v155 offset:16384
	ds_read_b128 v[196:199], v155 offset:17408
	ds_read_b128 v[200:203], v155 offset:18432
	ds_read_b128 v[204:207], v155 offset:19456
	ds_read_b128 v[208:211], v155 offset:20480
	ds_read_b128 v[212:215], v155 offset:21504
	ds_read_b128 v[216:219], v155 offset:22528
	ds_read_b128 v[220:223], v155 offset:23552
	global_load_lds_dwordx4 v[184:185], off
	s_add_i32 m0, s20, 0x2000
	s_add_u32 s28, s70, 0x80000
	v_lshl_add_u64 v[224:225], s[70:71], 0, v[140:141]
	s_addc_u32 s29, s71, 0
	s_add_i32 s5, s5, s76
	global_load_lds_dwordx4 v[224:225], off
	v_lshl_add_u64 v[226:227], s[28:29], 0, v[176:177]
	s_mov_b32 m0, s5
	v_lshl_add_u64 v[238:239], s[72:73], 0, v[138:139]
	global_load_lds_dwordx4 v[226:227], off
	v_lshl_add_u64 v[226:227], s[28:29], 0, v[140:141]
	s_add_i32 m0, s5, 0x2000
	s_nop 0
	global_load_lds_dwordx4 v[226:227], off
	v_lshl_add_u64 v[226:227], s[72:73], 0, v[136:137]
	s_waitcnt vmcnt(6)
	s_waitcnt lgkmcnt(0)
	s_barrier
; #define PG8_STAGE(bufoff, gbase, voff) do { _Pragma("unroll") for (int _i = 0; _i < 2; ++_i) \
;         __builtin_amdgcn_global_load_lds((const unsigned*)((const char*)(gbase) + (voff)[_i]), (LAS unsigned*)(lds + (bufoff) + ldsw + _i * 8192), 16, 0, 0); } while (0)
; #define PG8_LDA(dst, b, h) do { _Pragma("unroll") for (int m = 0; m < 4; ++m) _Pragma("unroll") for (int k = 0; k < 2; ++k) dst[m][k] = *(const LAS bf16x8*)(lds + PG8_SA(b, h) + aoff + m * 2048 + k * 1024); } while (0)
; #define PG8_LDB(dst, b, h) do { _Pragma("unroll") for (int n = 0; n < 2; ++n) _Pragma("unroll") for (int k = 0; k < 2; ++k) dst[n][k] = *(const LAS bf16x8*)(lds + PG8_SB(b, h) + boff + n * 2048 + k * 1024); } while (0)
; #define PG8_MMA(ai, bj, At, Bt) do { __builtin_amdgcn_s_setprio(1); _Pragma("unroll") for (int m = 0; m < 4; ++m) _Pragma("unroll") for (int n = 0; n < 2; ++n) _Pragma("unroll") for (int k = 0; k < 2; ++k) \
;         acc[ai][bj][m][n] = __builtin_amdgcn_mfma_f32_16x16x32_bf16(Bt[n][k], At[m][k], acc[ai][bj][m][n], 0, 0, 0); __builtin_amdgcn_s_setprio(0); } while (0)
; #define PG8_WAIT_V(n) asm volatile("s_waitcnt vmcnt(" #n ")" ::: "memory")
; #define PG8_WAIT_L(n) asm volatile("s_waitcnt lgkmcnt(" #n ")" ::: "memory")
; #define PG8_BAR __builtin_amdgcn_s_barrier()
; #define PG8_SCHED __builtin_amdgcn_sched_barrier(0)
; template <class Epi>
; __device__ __forceinline__ void gemm_phase(LAS unsigned char* lds, const Gemm g, const StaticOrder& S, const Epi& E, const int tid) {
;     ...
;             PG8_WAIT_V(8); PG8_WAIT_L(0); PG8_BAR; PG8_MMA(1, 0, At, B0); PG8_MMA(1, 1, At, B1); PG8_BAR; PG8_SCHED;
;             PG8_LDB(B0, 1, 0); PG8_LDB(B1, 1, 1); PG8_SCHED; PG8_LDA(At, 1, 0); PG8_STAGE(PG8_SA(0, 1), a2 + hstep, voffA);
;             PG8_WAIT_V(8); PG8_WAIT_L(0); PG8_BAR; PG8_MMA(0, 0, At, B0); PG8_MMA(0, 1, At, B1); PG8_BAR; PG8_SCHED;
	s_setprio 1
	s_waitcnt lgkmcnt(0)
	v_mfma_f32_16x16x32_bf16 v[92:95], v[128:131], v[192:195], v[92:95]
	v_mfma_f32_16x16x32_bf16 v[88:91], v[146:149], v[192:195], v[88:91]
	v_mfma_f32_16x16x32_bf16 v[84:87], v[128:131], v[200:203], v[84:87]
	v_mfma_f32_16x16x32_bf16 v[80:83], v[146:149], v[200:203], v[80:83]
	v_mfma_f32_16x16x32_bf16 v[76:79], v[128:131], v[208:211], v[76:79]
	v_mfma_f32_16x16x32_bf16 v[72:75], v[146:149], v[208:211], v[72:75]
	v_mfma_f32_16x16x32_bf16 v[68:71], v[128:131], v[216:219], v[68:71]
	v_mfma_f32_16x16x32_bf16 v[64:67], v[146:149], v[216:219], v[64:67]
	v_mfma_f32_16x16x32_bf16 v[92:95], v[132:135], v[196:199], v[92:95]
	v_mfma_f32_16x16x32_bf16 v[88:91], v[156:159], v[196:199], v[88:91]
	v_mfma_f32_16x16x32_bf16 v[84:87], v[132:135], v[204:207], v[84:87]
	v_mfma_f32_16x16x32_bf16 v[80:83], v[156:159], v[204:207], v[80:83]
	v_mfma_f32_16x16x32_bf16 v[76:79], v[132:135], v[212:215], v[76:79]
	v_mfma_f32_16x16x32_bf16 v[72:75], v[156:159], v[212:215], v[72:75]
	v_mfma_f32_16x16x32_bf16 v[68:71], v[132:135], v[220:223], v[68:71]
	v_mfma_f32_16x16x32_bf16 v[64:67], v[156:159], v[220:223], v[64:67]
	s_setprio 0
	s_setprio 1
	v_mfma_f32_16x16x32_bf16 v[28:31], v[160:163], v[192:195], v[28:31]
	v_mfma_f32_16x16x32_bf16 v[24:27], v[168:171], v[192:195], v[24:27]
	v_mfma_f32_16x16x32_bf16 v[20:23], v[160:163], v[200:203], v[20:23]
	v_mfma_f32_16x16x32_bf16 v[16:19], v[168:171], v[200:203], v[16:19]
	v_mfma_f32_16x16x32_bf16 v[12:15], v[160:163], v[208:211], v[12:15]
	v_mfma_f32_16x16x32_bf16 v[8:11], v[168:171], v[208:211], v[8:11]
	v_mfma_f32_16x16x32_bf16 v[4:7], v[160:163], v[216:219], v[4:7]
	v_mfma_f32_16x16x32_bf16 v[0:3], v[168:171], v[216:219], v[0:3]
	v_mfma_f32_16x16x32_bf16 v[28:31], v[164:167], v[196:199], v[28:31]
	v_mfma_f32_16x16x32_bf16 v[24:27], v[172:175], v[196:199], v[24:27]
	v_mfma_f32_16x16x32_bf16 v[20:23], v[164:167], v[204:207], v[20:23]
	v_mfma_f32_16x16x32_bf16 v[16:19], v[172:175], v[204:207], v[16:19]
	v_mfma_f32_16x16x32_bf16 v[12:15], v[164:167], v[212:215], v[12:15]
	v_mfma_f32_16x16x32_bf16 v[8:11], v[172:175], v[212:215], v[8:11]
	v_mfma_f32_16x16x32_bf16 v[4:7], v[164:167], v[220:223], v[4:7]
	v_mfma_f32_16x16x32_bf16 v[0:3], v[172:175], v[220:223], v[0:3]
	s_setprio 0
	s_barrier
	s_add_i32 s5, 0, 0x18000
	s_add_i32 s20, 0, 0x1c000
	v_add_u32_e32 v156, s5, v154
	v_add_u32_e32 v172, s20, v154
	ds_read_b128 v[128:131], v156
	ds_read_b128 v[132:135], v156 offset:1024
	ds_read_b128 v[146:149], v156 offset:2048
	ds_read_b128 v[156:159], v156 offset:3072
	ds_read_b128 v[160:163], v172
	ds_read_b128 v[164:167], v172 offset:1024
	ds_read_b128 v[168:171], v172 offset:2048
	ds_read_b128 v[172:175], v172 offset:3072
	s_add_u32 s28, s72, 0x80000
	s_addc_u32 s29, s73, 0
	s_mov_b32 m0, s77
	s_nop 0
	global_load_lds_dwordx4 v[226:227], off
	s_mov_b32 m0, s78
	s_nop 0
	global_load_lds_dwordx4 v[238:239], off
	s_mov_b32 m0, s79
	v_lshl_add_u64 v[240:241], s[28:29], 0, v[136:137]
	ds_read_b128 v[192:195], v155 offset:32768
	ds_read_b128 v[196:199], v155 offset:33792
	ds_read_b128 v[200:203], v155 offset:34816
	ds_read_b128 v[204:207], v155 offset:35840
	ds_read_b128 v[208:211], v155 offset:36864
	ds_read_b128 v[212:215], v155 offset:37888
	ds_read_b128 v[216:219], v155 offset:38912
	ds_read_b128 v[220:223], v155 offset:39936
	global_load_lds_dwordx4 v[240:241], off
	v_lshl_add_u64 v[240:241], s[28:29], 0, v[138:139]
	s_mov_b32 m0, s80
	s_nop 0
	global_load_lds_dwordx4 v[240:241], off
	s_waitcnt vmcnt(8)
	s_waitcnt lgkmcnt(0)
	s_barrier
	s_setprio 1
	s_waitcnt lgkmcnt(0)
	v_mfma_f32_16x16x32_bf16 v[124:127], v[128:131], v[192:195], v[124:127]
	v_mfma_f32_16x16x32_bf16 v[120:123], v[146:149], v[192:195], v[120:123]
	v_mfma_f32_16x16x32_bf16 v[116:119], v[128:131], v[200:203], v[116:119]
	v_mfma_f32_16x16x32_bf16 v[112:115], v[146:149], v[200:203], v[112:115]
	v_mfma_f32_16x16x32_bf16 v[108:111], v[128:131], v[208:211], v[108:111]
	v_mfma_f32_16x16x32_bf16 v[104:107], v[146:149], v[208:211], v[104:107]
	v_mfma_f32_16x16x32_bf16 v[100:103], v[128:131], v[216:219], v[100:103]
	v_mfma_f32_16x16x32_bf16 v[96:99], v[146:149], v[216:219], v[96:99]
	v_mfma_f32_16x16x32_bf16 v[124:127], v[132:135], v[196:199], v[124:127]
	v_mfma_f32_16x16x32_bf16 v[120:123], v[156:159], v[196:199], v[120:123]
	v_mfma_f32_16x16x32_bf16 v[116:119], v[132:135], v[204:207], v[116:119]
	v_mfma_f32_16x16x32_bf16 v[112:115], v[156:159], v[204:207], v[112:115]
	v_mfma_f32_16x16x32_bf16 v[108:111], v[132:135], v[212:215], v[108:111]
	v_mfma_f32_16x16x32_bf16 v[104:107], v[156:159], v[212:215], v[104:107]
	v_mfma_f32_16x16x32_bf16 v[100:103], v[132:135], v[220:223], v[100:103]
	v_mfma_f32_16x16x32_bf16 v[96:99], v[156:159], v[220:223], v[96:99]
	s_setprio 0
	s_setprio 1
	v_mfma_f32_16x16x32_bf16 v[60:63], v[160:163], v[192:195], v[60:63]
	v_mfma_f32_16x16x32_bf16 v[56:59], v[168:171], v[192:195], v[56:59]
	v_mfma_f32_16x16x32_bf16 v[52:55], v[160:163], v[200:203], v[52:55]
	v_mfma_f32_16x16x32_bf16 v[48:51], v[168:171], v[200:203], v[48:51]
	v_mfma_f32_16x16x32_bf16 v[44:47], v[160:163], v[208:211], v[44:47]
	v_mfma_f32_16x16x32_bf16 v[40:43], v[168:171], v[208:211], v[40:43]
	v_mfma_f32_16x16x32_bf16 v[36:39], v[160:163], v[216:219], v[36:39]
	v_mfma_f32_16x16x32_bf16 v[32:35], v[168:171], v[216:219], v[32:35]
	v_mfma_f32_16x16x32_bf16 v[60:63], v[164:167], v[196:199], v[60:63]
	v_mfma_f32_16x16x32_bf16 v[56:59], v[172:175], v[196:199], v[56:59]
	v_mfma_f32_16x16x32_bf16 v[52:55], v[164:167], v[204:207], v[52:55]
	v_mfma_f32_16x16x32_bf16 v[48:51], v[172:175], v[204:207], v[48:51]
	v_mfma_f32_16x16x32_bf16 v[44:47], v[164:167], v[212:215], v[44:47]
	v_mfma_f32_16x16x32_bf16 v[40:43], v[172:175], v[212:215], v[40:43]
	v_mfma_f32_16x16x32_bf16 v[36:39], v[164:167], v[220:223], v[36:39]
	v_mfma_f32_16x16x32_bf16 v[32:35], v[172:175], v[220:223], v[32:35]
	s_setprio 0
	s_barrier
; #define PG8_STAGE(bufoff, gbase, voff) do { _Pragma("unroll") for (int _i = 0; _i < 2; ++_i) \
;         __builtin_amdgcn_global_load_lds((const unsigned*)((const char*)(gbase) + (voff)[_i]), (LAS unsigned*)(lds + (bufoff) + ldsw + _i * 8192), 16, 0, 0); } while (0)
; #define PG8_LDA(dst, b, h) do { _Pragma("unroll") for (int m = 0; m < 4; ++m) _Pragma("unroll") for (int k = 0; k < 2; ++k) dst[m][k] = *(const LAS bf16x8*)(lds + PG8_SA(b, h) + aoff + m * 2048 + k * 1024); } while (0)
; #define PG8_MMA(ai, bj, At, Bt) do { __builtin_amdgcn_s_setprio(1); _Pragma("unroll") for (int m = 0; m < 4; ++m) _Pragma("unroll") for (int n = 0; n < 2; ++n) _Pragma("unroll") for (int k = 0; k < 2; ++k) \
;         acc[ai][bj][m][n] = __builtin_amdgcn_mfma_f32_16x16x32_bf16(Bt[n][k], At[m][k], acc[ai][bj][m][n], 0, 0, 0); __builtin_amdgcn_s_setprio(0); } while (0)
; #define PG8_WAIT_V(n) asm volatile("s_waitcnt vmcnt(" #n ")" ::: "memory")
; #define PG8_WAIT_L(n) asm volatile("s_waitcnt lgkmcnt(" #n ")" ::: "memory")
; #define PG8_BAR __builtin_amdgcn_s_barrier()
; #define PG8_SCHED __builtin_amdgcn_sched_barrier(0)
; template <class Epi>
; __device__ __forceinline__ void gemm_phase(LAS unsigned char* lds, const Gemm g, const StaticOrder& S, const Epi& E, const int tid) {
;     ...
;             PG8_LDA(At, 1, 1); PG8_STAGE(PG8_SB(1, 0), b3, voffB); PG8_STAGE(PG8_SB(1, 1), b3 + hstep, voffB); PG8_STAGE(PG8_SA(1, 0), a3, voffA);
;             PG8_WAIT_V(8); PG8_WAIT_L(0); PG8_BAR; PG8_MMA(1, 0, At, B0); PG8_MMA(1, 1, At, B1); PG8_BAR; PG8_SCHED;
;         }
;         if (wr == 0) PG8_BAR;
	s_add_i32 s5, s5, s76
	v_lshl_add_u64 v[184:185], v[184:185], 0, s[0:1]
	s_mov_b32 m0, s5
	ds_read_b128 v[192:195], v155 offset:49152
	ds_read_b128 v[196:199], v155 offset:50176
	ds_read_b128 v[200:203], v155 offset:51200
	ds_read_b128 v[204:207], v155 offset:52224
	ds_read_b128 v[208:211], v155 offset:53248
	ds_read_b128 v[212:215], v155 offset:54272
	ds_read_b128 v[216:219], v155 offset:55296
	ds_read_b128 v[220:223], v155 offset:56320
	global_load_lds_dwordx4 v[184:185], off
	s_add_i32 m0, s5, 0x2000
	s_add_u32 s28, s70, 0x80080
	v_lshl_add_u64 v[184:185], v[224:225], 0, s[0:1]
	s_addc_u32 s29, s71, 0
	s_add_i32 s5, s20, s76
	global_load_lds_dwordx4 v[184:185], off
	v_lshl_add_u64 v[184:185], s[28:29], 0, v[176:177]
	s_mov_b32 m0, s5
	s_nop 0
	global_load_lds_dwordx4 v[184:185], off
	v_lshl_add_u64 v[184:185], s[28:29], 0, v[140:141]
	s_add_i32 m0, s5, 0x2000
	s_nop 0
	global_load_lds_dwordx4 v[184:185], off
	v_lshl_add_u64 v[184:185], v[226:227], 0, s[0:1]
	s_mov_b32 m0, s82
	s_nop 0
	global_load_lds_dwordx4 v[184:185], off
	v_lshl_add_u64 v[184:185], v[238:239], 0, s[0:1]
	s_mov_b32 m0, s84
	s_nop 0
	global_load_lds_dwordx4 v[184:185], off
	s_waitcnt vmcnt(8)
	s_waitcnt lgkmcnt(0)
	s_barrier
	s_setprio 1
	s_waitcnt lgkmcnt(0)
	v_mfma_f32_16x16x32_bf16 v[92:95], v[128:131], v[192:195], v[92:95]
	v_mfma_f32_16x16x32_bf16 v[88:91], v[146:149], v[192:195], v[88:91]
	v_mfma_f32_16x16x32_bf16 v[84:87], v[128:131], v[200:203], v[84:87]
	v_mfma_f32_16x16x32_bf16 v[80:83], v[146:149], v[200:203], v[80:83]
	v_mfma_f32_16x16x32_bf16 v[76:79], v[128:131], v[208:211], v[76:79]
	v_mfma_f32_16x16x32_bf16 v[72:75], v[146:149], v[208:211], v[72:75]
	v_mfma_f32_16x16x32_bf16 v[68:71], v[128:131], v[216:219], v[68:71]
	v_mfma_f32_16x16x32_bf16 v[64:67], v[146:149], v[216:219], v[64:67]
	v_mfma_f32_16x16x32_bf16 v[92:95], v[132:135], v[196:199], v[92:95]
	v_mfma_f32_16x16x32_bf16 v[88:91], v[156:159], v[196:199], v[88:91]
	v_mfma_f32_16x16x32_bf16 v[84:87], v[132:135], v[204:207], v[84:87]
	v_mfma_f32_16x16x32_bf16 v[80:83], v[156:159], v[204:207], v[80:83]
	v_mfma_f32_16x16x32_bf16 v[76:79], v[132:135], v[212:215], v[76:79]
	v_mfma_f32_16x16x32_bf16 v[72:75], v[156:159], v[212:215], v[72:75]
	v_mfma_f32_16x16x32_bf16 v[68:71], v[132:135], v[220:223], v[68:71]
	v_mfma_f32_16x16x32_bf16 v[64:67], v[156:159], v[220:223], v[64:67]
	s_setprio 0
	s_setprio 1
	v_mfma_f32_16x16x32_bf16 v[28:31], v[160:163], v[192:195], v[28:31]
	v_mfma_f32_16x16x32_bf16 v[24:27], v[168:171], v[192:195], v[24:27]
	v_mfma_f32_16x16x32_bf16 v[20:23], v[160:163], v[200:203], v[20:23]
	v_mfma_f32_16x16x32_bf16 v[16:19], v[168:171], v[200:203], v[16:19]
	v_mfma_f32_16x16x32_bf16 v[12:15], v[160:163], v[208:211], v[12:15]
	v_mfma_f32_16x16x32_bf16 v[8:11], v[168:171], v[208:211], v[8:11]
	v_mfma_f32_16x16x32_bf16 v[4:7], v[160:163], v[216:219], v[4:7]
	v_mfma_f32_16x16x32_bf16 v[0:3], v[168:171], v[216:219], v[0:3]
	v_mfma_f32_16x16x32_bf16 v[28:31], v[164:167], v[196:199], v[28:31]
	v_mfma_f32_16x16x32_bf16 v[24:27], v[172:175], v[196:199], v[24:27]
	v_mfma_f32_16x16x32_bf16 v[20:23], v[164:167], v[204:207], v[20:23]
	v_mfma_f32_16x16x32_bf16 v[16:19], v[172:175], v[204:207], v[16:19]
	v_mfma_f32_16x16x32_bf16 v[12:15], v[164:167], v[212:215], v[12:15]
	v_mfma_f32_16x16x32_bf16 v[8:11], v[172:175], v[212:215], v[8:11]
	v_mfma_f32_16x16x32_bf16 v[4:7], v[164:167], v[220:223], v[4:7]
	v_mfma_f32_16x16x32_bf16 v[0:3], v[172:175], v[220:223], v[0:3]
	s_setprio 0
	s_barrier
	s_add_i32 vcc_hi, vcc_hi, 2
	s_add_u32 s68, s68, 0x100
	s_addc_u32 s69, s69, 0
	s_add_u32 s95, s95, 0x100
	s_addc_u32 vcc_lo, vcc_lo, 0
	s_cmp_gt_u32 vcc_hi, 29
	s_cbranch_scc0 .LBB0_584
	s_and_b64 vcc, exec, s[56:57]
	s_cbranch_vccz .LBB0_587
	s_barrier

; __global__ void __launch_bounds__(512, 2) mega_fwd(Args args) {
;     ...
;                 for (int it = bx; it < DEPTH * 96; it += G) {
;                     const int l = it / 96, n0 = (it % 96) * 64;
;                     const float* W = args.in[5] + (size_t)l * DM * 6144 + n0 + lane;
;                     float a0 = 0.f, a1 = 0.f, a2 = 0.f, a3 = 0.f, a4 = 0.f;
;                     const int kb = wave * 256;
; #pragma unroll 8
;                     for (int k = 0; k < 256; ++k) { const float wv = W[(size_t)(kb + k) * 6144];
;                         a0 += sc[kb + k] * wv; a1 += sc[DM + kb + k] * wv; a2 += sc[2 * DM + kb + k] * wv; a3 += sc[3 * DM + kb + k] * wv; a4 += sc[4 * DM + kb + k] * wv; }
.LBB0_742:
	v_lshl_add_u64 v[12:13], v[2:3], 0, s[14:15]
	v_add_co_u32_e64 v14, s[44:45], s82, v12
	global_load_dword v52, v[12:13], off
	s_nop 0
	v_addc_co_u32_e64 v15, s[44:45], 0, v13, s[44:45]
	v_add_co_u32_e64 v16, s[44:45], s77, v12
	v_mov_b32_e32 v11, s5
	s_nop 0
	v_addc_co_u32_e64 v17, s[44:45], 0, v13, s[44:45]
	v_add_co_u32_e64 v18, s[44:45], s85, v12
	s_add_u32 s14, s14, 0x30000
	s_nop 0
	v_addc_co_u32_e64 v19, s[44:45], 0, v13, s[44:45]
	v_add_co_u32_e64 v20, s[44:45], s76, v12
	s_addc_u32 s15, s15, 0
	s_nop 0
	v_addc_co_u32_e64 v21, s[44:45], 0, v13, s[44:45]
	v_add_co_u32_e64 v22, s[44:45], s92, v12
	s_add_i32 s5, s5, 32
	s_nop 0
	v_addc_co_u32_e64 v23, s[44:45], 0, v13, s[44:45]
	v_add_co_u32_e64 v24, s[44:45], s91, v12
	s_nop 0
	s_nop 0
	v_addc_co_u32_e64 v25, s[44:45], 0, v13, s[44:45]
	v_add_co_u32_e64 v12, s[44:45], s94, v12
	s_nop 1
	v_addc_co_u32_e64 v13, s[44:45], 0, v13, s[44:45]
	global_load_dword v54, v[14:15], off
	global_load_dword v56, v[16:17], off
	global_load_dword v58, v[18:19], off
	global_load_dword v60, v[20:21], off
	global_load_dword v62, v[22:23], off
	global_load_dword v64, v[24:25], off
	global_load_dword v66, v[12:13], off
	v_lshl_add_u64 v[26:27], v[2:3], 0, s[14:15]
	v_add_co_u32_e64 v28, s[44:45], s82, v26
	global_load_dword v112, v[26:27], off
	s_nop 0
	v_addc_co_u32_e64 v29, s[44:45], 0, v27, s[44:45]
	v_add_co_u32_e64 v30, s[44:45], s77, v26
	s_nop 0
	s_nop 0
	v_addc_co_u32_e64 v31, s[44:45], 0, v27, s[44:45]
	v_add_co_u32_e64 v32, s[44:45], s85, v26
	s_add_u32 s14, s14, 0x30000
	s_nop 0
	v_addc_co_u32_e64 v33, s[44:45], 0, v27, s[44:45]
	v_add_co_u32_e64 v34, s[44:45], s76, v26
	s_addc_u32 s15, s15, 0
	s_nop 0
	v_addc_co_u32_e64 v35, s[44:45], 0, v27, s[44:45]
	v_add_co_u32_e64 v36, s[44:45], s92, v26
	s_add_i32 s5, s5, 32
	s_nop 0
	v_addc_co_u32_e64 v37, s[44:45], 0, v27, s[44:45]
	v_add_co_u32_e64 v38, s[44:45], s91, v26
	s_nop 0
	s_nop 0
	v_addc_co_u32_e64 v39, s[44:45], 0, v27, s[44:45]
	v_add_co_u32_e64 v26, s[44:45], s94, v26
	s_nop 1
	v_addc_co_u32_e64 v27, s[44:45], 0, v27, s[44:45]
	global_load_dword v114, v[28:29], off
	global_load_dword v116, v[30:31], off
	global_load_dword v118, v[32:33], off
	global_load_dword v120, v[34:35], off
	global_load_dword v122, v[36:37], off
	global_load_dword v124, v[38:39], off
	global_load_dword v126, v[26:27], off
	ds_read_b128 v[12:15], v11
	ds_read_b128 v[16:19], v11 offset:16
	ds_read_b128 v[20:23], v11 offset:8192
	ds_read_b128 v[24:27], v11 offset:8208
	ds_read_b128 v[28:31], v11 offset:16384
	ds_read_b128 v[32:35], v11 offset:16400
	ds_read_b128 v[36:39], v11 offset:24576
	ds_read_b128 v[40:43], v11 offset:24592
	ds_read_b128 v[44:47], v11 offset:32768
	ds_read_b128 v[48:51], v11 offset:32784
	s_waitcnt lgkmcnt(9)
	v_mov_b32_e32 v68, v12
	s_waitcnt lgkmcnt(7)
	v_mov_b32_e32 v69, v20
	v_mov_b32_e32 v20, v13
	v_mov_b32_e32 v12, v14
	v_mov_b32_e32 v13, v22
	v_mov_b32_e32 v22, v15
	s_waitcnt lgkmcnt(5)
	v_mov_b32_e32 v14, v28
	s_waitcnt lgkmcnt(3)
	v_mov_b32_e32 v15, v36
	v_mov_b32_e32 v36, v29
	v_mov_b32_e32 v28, v30
	v_mov_b32_e32 v29, v38
	v_mov_b32_e32 v38, v31
	v_mov_b32_e32 v30, v16
	v_mov_b32_e32 v31, v24
	v_mov_b32_e32 v24, v17
	v_mov_b32_e32 v16, v18
	v_mov_b32_e32 v17, v26
	v_mov_b32_e32 v26, v19
	v_mov_b32_e32 v18, v32
	s_waitcnt lgkmcnt(2)
	v_mov_b32_e32 v19, v40
	v_mov_b32_e32 v40, v33
	v_mov_b32_e32 v32, v34
	v_mov_b32_e32 v33, v42
	v_mov_b32_e32 v42, v35
	s_waitcnt vmcnt(15)
	v_pk_fma_f32 v[4:5], v[52:53], v[68:69], v[4:5] op_sel_hi:[0,1,1]
	v_pk_fma_f32 v[6:7], v[52:53], v[14:15], v[6:7] op_sel_hi:[0,1,1]
	s_waitcnt lgkmcnt(1)
	v_fmac_f32_e32 v10, v52, v44
	s_waitcnt vmcnt(14)
	v_pk_fma_f32 v[4:5], v[54:55], v[20:21], v[4:5] op_sel_hi:[0,1,1]
	v_pk_fma_f32 v[6:7], v[54:55], v[36:37], v[6:7] op_sel_hi:[0,1,1]
	v_fmac_f32_e32 v10, v54, v45
	s_waitcnt vmcnt(13)
	v_pk_fma_f32 v[4:5], v[56:57], v[12:13], v[4:5] op_sel_hi:[0,1,1]
	v_pk_fma_f32 v[6:7], v[56:57], v[28:29], v[6:7] op_sel_hi:[0,1,1]
	v_fmac_f32_e32 v10, v56, v46
	s_waitcnt vmcnt(12)
	v_pk_fma_f32 v[4:5], v[58:59], v[22:23], v[4:5] op_sel_hi:[0,1,1]
	v_pk_fma_f32 v[6:7], v[58:59], v[38:39], v[6:7] op_sel_hi:[0,1,1]
	v_fmac_f32_e32 v10, v58, v47
	s_waitcnt vmcnt(11)
	v_pk_fma_f32 v[4:5], v[60:61], v[30:31], v[4:5] op_sel_hi:[0,1,1]
	v_pk_fma_f32 v[6:7], v[60:61], v[18:19], v[6:7] op_sel_hi:[0,1,1]
	s_waitcnt lgkmcnt(0)
	v_fmac_f32_e32 v10, v60, v48
	s_waitcnt vmcnt(10)
	v_pk_fma_f32 v[4:5], v[62:63], v[24:25], v[4:5] op_sel_hi:[0,1,1]
	v_pk_fma_f32 v[6:7], v[62:63], v[40:41], v[6:7] op_sel_hi:[0,1,1]
	v_fmac_f32_e32 v10, v62, v49
	s_waitcnt vmcnt(9)
	v_pk_fma_f32 v[4:5], v[64:65], v[16:17], v[4:5] op_sel_hi:[0,1,1]
	v_pk_fma_f32 v[6:7], v[64:65], v[32:33], v[6:7] op_sel_hi:[0,1,1]
	v_fmac_f32_e32 v10, v64, v50
	s_waitcnt vmcnt(8)
; __global__ void __launch_bounds__(512, 2) mega_fwd(Args args) {
;     ...
;                     for (int k = 0; k < 256; ++k) { const float wv = W[(size_t)(kb + k) * 6144];
;                         a0 += sc[kb + k] * wv; a1 += sc[DM + kb + k] * wv; a2 += sc[2 * DM + kb + k] * wv; a3 += sc[3 * DM + kb + k] * wv; a4 += sc[4 * DM + kb + k] * wv; }
;                     red[(wave * 5 + 0) * 64 + lane] = a0; red[(wave * 5 + 1) * 64 + lane] = a1; red[(wave * 5 + 2) * 64 + lane] = a2; red[(wave * 5 + 3) * 64 + lane] = a3; red[(wave * 5 + 4) * 64 + lane] = a4;
;                     __syncthreads();
;                     if (tid < 320) { const int i = tid >> 6; float s = 0.f;
;                         for (int w8 = 0; w8 < 8; ++w8) s += red[(w8 * 5 + i) * 64 + lane];
;                         MOD[((size_t)l * 5 + i) * 6144 + n0 + lane] = s + args.in[6][(size_t)l * 6144 + n0 + lane]; }
;                     __syncthreads();
	v_pk_fma_f32 v[4:5], v[66:67], v[26:27], v[4:5] op_sel_hi:[0,1,1]
	v_pk_fma_f32 v[6:7], v[66:67], v[42:43], v[6:7] op_sel_hi:[0,1,1]
	v_fmac_f32_e32 v10, v66, v51
	ds_read_b128 v[12:15], v11 offset:32
	ds_read_b128 v[16:19], v11 offset:48
	ds_read_b128 v[20:23], v11 offset:8224
	ds_read_b128 v[24:27], v11 offset:8240
	ds_read_b128 v[28:31], v11 offset:16416
	ds_read_b128 v[32:35], v11 offset:16432
	ds_read_b128 v[36:39], v11 offset:24608
	ds_read_b128 v[40:43], v11 offset:24624
	ds_read_b128 v[44:47], v11 offset:32800
	ds_read_b128 v[48:51], v11 offset:32816
	s_waitcnt lgkmcnt(9)
	v_mov_b32_e32 v68, v12
	s_waitcnt lgkmcnt(7)
	v_mov_b32_e32 v69, v20
	v_mov_b32_e32 v20, v13
	v_mov_b32_e32 v12, v14
	v_mov_b32_e32 v13, v22
	v_mov_b32_e32 v22, v15
	s_waitcnt lgkmcnt(5)
	v_mov_b32_e32 v14, v28
	s_waitcnt lgkmcnt(3)
	v_mov_b32_e32 v15, v36
	v_mov_b32_e32 v36, v29
	v_mov_b32_e32 v28, v30
	v_mov_b32_e32 v29, v38
	v_mov_b32_e32 v38, v31
	v_mov_b32_e32 v30, v16
	v_mov_b32_e32 v31, v24
	v_mov_b32_e32 v24, v17
	v_mov_b32_e32 v16, v18
	v_mov_b32_e32 v17, v26
	v_mov_b32_e32 v26, v19
	v_mov_b32_e32 v18, v32
	s_waitcnt lgkmcnt(2)
	v_mov_b32_e32 v19, v40
	v_mov_b32_e32 v40, v33
	v_mov_b32_e32 v32, v34
	v_mov_b32_e32 v33, v42
	v_mov_b32_e32 v42, v35
	s_waitcnt vmcnt(7)
	v_pk_fma_f32 v[4:5], v[112:113], v[68:69], v[4:5] op_sel_hi:[0,1,1]
	v_pk_fma_f32 v[6:7], v[112:113], v[14:15], v[6:7] op_sel_hi:[0,1,1]
	s_waitcnt lgkmcnt(1)
	v_fmac_f32_e32 v10, v112, v44
	s_waitcnt vmcnt(6)
	v_pk_fma_f32 v[4:5], v[114:115], v[20:21], v[4:5] op_sel_hi:[0,1,1]
	v_pk_fma_f32 v[6:7], v[114:115], v[36:37], v[6:7] op_sel_hi:[0,1,1]
	v_fmac_f32_e32 v10, v114, v45
	s_waitcnt vmcnt(5)
	v_pk_fma_f32 v[4:5], v[116:117], v[12:13], v[4:5] op_sel_hi:[0,1,1]
	v_pk_fma_f32 v[6:7], v[116:117], v[28:29], v[6:7] op_sel_hi:[0,1,1]
	v_fmac_f32_e32 v10, v116, v46
	s_waitcnt vmcnt(4)
	v_pk_fma_f32 v[4:5], v[118:119], v[22:23], v[4:5] op_sel_hi:[0,1,1]
	v_pk_fma_f32 v[6:7], v[118:119], v[38:39], v[6:7] op_sel_hi:[0,1,1]
	v_fmac_f32_e32 v10, v118, v47
	s_waitcnt vmcnt(3)
	v_pk_fma_f32 v[4:5], v[120:121], v[30:31], v[4:5] op_sel_hi:[0,1,1]
	v_pk_fma_f32 v[6:7], v[120:121], v[18:19], v[6:7] op_sel_hi:[0,1,1]
	s_waitcnt lgkmcnt(0)
	v_fmac_f32_e32 v10, v120, v48
	s_waitcnt vmcnt(2)
	v_pk_fma_f32 v[4:5], v[122:123], v[24:25], v[4:5] op_sel_hi:[0,1,1]
	v_pk_fma_f32 v[6:7], v[122:123], v[40:41], v[6:7] op_sel_hi:[0,1,1]
	v_fmac_f32_e32 v10, v122, v49
	s_waitcnt vmcnt(1)
	v_pk_fma_f32 v[4:5], v[124:125], v[16:17], v[4:5] op_sel_hi:[0,1,1]
	v_pk_fma_f32 v[6:7], v[124:125], v[32:33], v[6:7] op_sel_hi:[0,1,1]
	v_fmac_f32_e32 v10, v124, v50
	s_waitcnt vmcnt(0)
	v_pk_fma_f32 v[4:5], v[126:127], v[26:27], v[4:5] op_sel_hi:[0,1,1]
	v_pk_fma_f32 v[6:7], v[126:127], v[42:43], v[6:7] op_sel_hi:[0,1,1]
	v_fmac_f32_e32 v10, v126, v51
	s_cmp_eq_u32 s14, 0x600000
	s_cbranch_scc0 .LBB0_742
	ds_write2st64_b32 v8, v4, v5 offset1:1
	ds_write2st64_b32 v8, v6, v7 offset0:2 offset1:3
	ds_write_b32 v8, v10 offset:1024
	s_waitcnt lgkmcnt(0)
	s_barrier
	s_and_saveexec_b64 s[14:15], vcc
	s_cbranch_execz .LBB0_740
	v_readlane_b32 s44, v253, 61
	s_mul_i32 s10, s4, 0x6000
	v_readlane_b32 s56, v254, 9
	s_mul_hi_i32 s5, s4, 0x6000
	v_readlane_b32 s57, v254, 10
	s_add_u32 s10, s56, s10
	s_addc_u32 s5, s57, s5
	s_add_u32 s20, s10, s12
	s_addc_u32 s21, s5, s13
	global_load_dword v16, v176, s[20:21]
	ds_read2st64_b32 v[2:3], v9 offset1:5
	ds_read2st64_b32 v[4:5], v9 offset0:10 offset1:15
	ds_read2st64_b32 v[6:7], v9 offset0:20 offset1:25
	ds_read2st64_b32 v[10:11], v9 offset0:30 offset1:35
	v_mad_i64_i32 v[12:13], s[4:5], s4, 5, v[190:191]
	s_waitcnt lgkmcnt(3)
	v_add_f32_e32 v2, 0, v2
	v_add_f32_e32 v2, v2, v3
	s_waitcnt lgkmcnt(2)
	v_add_f32_e32 v2, v2, v4
	v_add_f32_e32 v2, v2, v5
	v_mov_b64_e32 v[14:15], s[88:89]
	s_waitcnt lgkmcnt(1)
	v_add_f32_e32 v2, v2, v6
	v_mad_u64_u32 v[14:15], s[4:5], v12, s82, v[14:15]
	v_add_f32_e32 v2, v2, v7
	v_mad_i32_i24 v15, v13, s82, v15
	s_waitcnt lgkmcnt(0)
	v_add_f32_e32 v2, v2, v10
	v_lshl_add_u64 v[12:13], v[14:15], 0, s[12:13]
	v_add_f32_e32 v2, v2, v11
	v_readlane_b32 s45, v253, 62
	v_readlane_b32 s46, v253, 63
	v_readlane_b32 s47, v254, 0
	v_readlane_b32 s48, v254, 1
	v_readlane_b32 s49, v254, 2
	v_readlane_b32 s50, v254, 3
	v_readlane_b32 s51, v254, 4
	v_readlane_b32 s52, v254, 5
	v_readlane_b32 s53, v254, 6
	v_readlane_b32 s54, v254, 7
	v_readlane_b32 s55, v254, 8
	v_readlane_b32 s58, v254, 11
	v_readlane_b32 s59, v254, 12
	s_waitcnt vmcnt(0)
	v_add_f32_e32 v4, v2, v16
	v_lshl_add_u64 v[2:3], v[12:13], 0, v[176:177]
	global_store_dword v[2:3], v4, off
	s_branch .LBB0_740
